# baseline (speedup 1.0000x reference)
; #define SCAN_BAR() do { asm volatile("s_waitcnt lgkmcnt(0)" ::: "memory"); __builtin_amdgcn_s_barrier(); asm volatile("" ::: "memory"); } while (0)
; __device__ __forceinline__ void scan_phase(const ScanArgs& s, char* shm) {
;     ...
;     } else if (wid < 6) {
;       const int yw = wid - 2, sw = yw & 1, tp = yw >> 1;
;       const int rr = lane >> 4, j = lane & 15, row = sw * 4 + rr;
;       u16* yp = s.Y + tokb * 1024 + colh + rg * 8 + (lane & 1) * 4;
;       SCAN_BAR();
.LBB0_154:
	s_andn2_saveexec_b64 s[60:61], s[74:75]
	s_cbranch_execz .LBB0_168
	s_setprio 2
	s_lshl_b64 s[62:63], s[62:63], 25
	s_add_u32 s62, s44, s62
	s_addc_u32 s63, s39, s63
	s_lshl_b32 s65, s65, 1
	s_add_u32 s62, s62, s65
	s_addc_u32 s63, s63, 0
	s_lshl_b32 s65, s64, 4
	s_add_u32 s62, s62, s65
	s_addc_u32 s63, s63, 0
	v_mov_b32_e32 v141, v133
	s_cmp_eq_u32 s64, 0
	v_lshl_add_u64 v[0:1], s[62:63], 0, v[140:141]
	s_cselect_b64 s[62:63], -1, 0
	s_waitcnt lgkmcnt(0)
	s_barrier
	s_and_b64 s[62:63], s[62:63], s[14:15]
	s_lshl_b32 s49, s49, 2
	s_add_u32 s66, s84, s49
	s_mov_b32 s65, 0
	s_addc_u32 s67, s85, 0
	s_movk_i32 s49, 0xffe0
	s_movk_i32 s64, 0xf000
	s_mov_b32 s79, 0
	s_branch .LBB0_157
